# last FFN's down-projection weight prep moved from phase 11 (critical) to phase 19's idle workgroups
# speedup vs baseline: 1.0137x; 1.0137x over previous
.LBB0_828:
	s_cmp_eq_u32 s86, 19
	s_mov_b64 s[18:19], -1
	s_mov_b32 s1, 0x10000
	s_mov_b32 s2, 0x16000
	s_movk_i32 s14, 0x57f
	s_mov_b32 s15, 0x2e8ba2e9
	s_mov_b32 s43, 0xb000
	s_mov_b32 s48, 0x37000
	s_movk_i32 s58, 0x5000
	s_movk_i32 s59, 0x41ff
	s_mov_b32 s62, 0x26000
	s_mov_b32 s63, 0x2c000
	s_mov_b32 s66, 0x3c000
	s_mov_b32 s67, 0x3e0f83e1
	s_movk_i32 s68, 0xaff
	s_mov_b32 s69, 0xb00000
	s_movk_i32 s72, 0x58
	s_mov_b32 s73, 0xffc0
	s_mov_b32 s74, 0x1b000
	s_mov_b32 s75, 0x21000
	s_mov_b32 s76, 0x31000
	s_mov_b32 s77, 0x42000
	s_mov_b32 s78, 0x47000
	s_mov_b32 s94, 0x4d000
	s_mov_b32 s95, 0x52000
	s_mov_b32 s96, 0x5d000
	s_mov_b32 s97, 0x63000
	v_readlane_b32 s8, v255, 3
	s_mov_b32 s31, s79
	v_mov_b32_e32 v0, v156
	v_readlane_b32 s9, v255, 4
	s_movk_i32 s55, 0xff00
	s_mov_b64 s[6:7], -1
	v_ashrrev_i32_e32 v5, 6, v0
	s_and_b64 vcc, exec, s[8:9]
	s_cbranch_vccz .LBB0_923
	s_and_b64 s[6:7], s[12:13], exec
	s_movk_i32 s0, 0x2100
	s_cselect_b32 s0, s0, 0x3180
	s_and_b64 s[6:7], s[16:17], exec
	s_cselect_b32 s36, 0xb00, s0
	s_and_b64 s[6:7], s[12:13], exec
	s_movk_i32 s0, 0x4200
	s_cselect_b32 s0, 0x3180, s0
	s_and_b64 s[6:7], s[16:17], exec
	s_cselect_b32 s4, 0x2100, s0
	s_and_b64 s[6:7], s[12:13], exec
	s_cselect_b32 s0, 0x4800, 0
	s_and_b64 s[6:7], s[16:17], exec
	s_cselect_b32 s0, 0x4200, s0
	s_and_b64 s[6:7], s[12:13], exec
	s_cselect_b32 s8, 0x5000, 0
	s_and_b64 s[6:7], s[16:17], exec
	s_cselect_b32 s6, 0x4800, s8
	s_sub_i32 s37, s4, s36
	s_sub_i32 s39, s6, s0
	v_lshl_add_u32 v42, s31, 3, v5
	v_mov_b32_e32 v3, v156
	s_add_i32 s39, s39, s37
	v_cmp_gt_i32_e32 vcc, s39, v42
	v_and_b32_e32 v43, 63, v3
	s_and_saveexec_b64 s[18:19], vcc
	s_cbranch_execz .LBB0_909
	v_lshlrev_b32_e32 v0, 8, v3
	v_and_b32_e32 v0, 0xffffc000, v0
	v_add_u32_e32 v1, 0, v0
	v_lshrrev_b32_e32 v0, 5, v43
	v_and_b32_e32 v2, 31, v3
	v_mul_u32_u24_e32 v4, 0x84, v0
	v_lshlrev_b32_e32 v6, 2, v2
	v_add3_u32 v44, v1, v4, v6
	v_lshlrev_b32_e32 v4, 3, v43
	v_and_b32_e32 v4, 56, v4
	v_lshlrev_b32_e32 v158, 1, v4
	v_lshrrev_b32_e32 v107, 3, v43
	v_lshl_add_u64 v[14:15], s[90:91], 0, v[158:159]
	s_mov_b64 s[6:7], 0x1080000
	v_mul_u32_u24_e32 v8, 0x84, v4
	v_lshl_add_u64 v[6:7], v[14:15], 0, s[6:7]
	v_lshlrev_b32_e32 v9, 2, v107
	s_mov_b64 s[6:7], 0x1680000
	v_add3_u32 v108, v1, v8, v9
	v_lshl_add_u64 v[8:9], v[14:15], 0, s[6:7]
	s_mov_b64 s[6:7], 0x6080000
	v_lshl_add_u64 v[10:11], v[14:15], 0, s[6:7]
	s_mov_b64 s[6:7], 0x5e80000
	v_lshl_add_u64 v[12:13], v[14:15], 0, s[6:7]
	s_mov_b64 s[6:7], 0x5c80000
	s_sub_i32 s47, s0, s37
	v_or_b32_e32 v45, 2, v0
	v_add_u32_e32 v46, 0x108, v44
	v_or_b32_e32 v47, 4, v0
	v_add_u32_e32 v48, 0x210, v44
	v_or_b32_e32 v49, 6, v0
	v_add_u32_e32 v50, 0x318, v44
	v_or_b32_e32 v51, 8, v0
	v_add_u32_e32 v52, 0x420, v44
	v_or_b32_e32 v53, 10, v0
	v_add_u32_e32 v54, 0x528, v44
	v_or_b32_e32 v55, 12, v0
	v_add_u32_e32 v56, 0x630, v44
	v_or_b32_e32 v57, 14, v0
	v_add_u32_e32 v58, 0x738, v44
	v_or_b32_e32 v59, 16, v0
	v_add_u32_e32 v60, 0x840, v44
	v_or_b32_e32 v61, 18, v0
	v_add_u32_e32 v62, 0x948, v44
	v_or_b32_e32 v63, 20, v0
	v_add_u32_e32 v64, 0xa50, v44
	v_or_b32_e32 v65, 22, v0
	v_add_u32_e32 v66, 0xb58, v44
	v_or_b32_e32 v67, 24, v0
	v_add_u32_e32 v68, 0xc60, v44
	v_or_b32_e32 v69, 26, v0
	v_add_u32_e32 v70, 0xd68, v44
	v_or_b32_e32 v71, 28, v0
	v_add_u32_e32 v72, 0xe70, v44
	v_or_b32_e32 v73, 30, v0
	v_add_u32_e32 v74, 0xf78, v44
	v_or_b32_e32 v75, 32, v0
	v_add_u32_e32 v76, 0x1080, v44
	v_or_b32_e32 v77, 34, v0
	v_add_u32_e32 v78, 0x1188, v44
	v_or_b32_e32 v79, 36, v0
	v_add_u32_e32 v80, 0x1290, v44
	v_or_b32_e32 v81, 38, v0
	v_add_u32_e32 v82, 0x1398, v44
	v_or_b32_e32 v83, 40, v0
	v_add_u32_e32 v84, 0x14a0, v44
	v_or_b32_e32 v85, 42, v0
	v_add_u32_e32 v86, 0x15a8, v44
	v_or_b32_e32 v87, 44, v0
	v_add_u32_e32 v88, 0x16b0, v44
	v_or_b32_e32 v89, 46, v0
	v_add_u32_e32 v90, 0x17b8, v44
	v_or_b32_e32 v91, 48, v0
	v_add_u32_e32 v92, 0x18c0, v44
	v_or_b32_e32 v93, 50, v0
	v_add_u32_e32 v94, 0x19c8, v44
	v_or_b32_e32 v95, 52, v0
	v_add_u32_e32 v96, 0x1ad0, v44
	v_or_b32_e32 v97, 54, v0
	v_add_u32_e32 v98, 0x1bd8, v44
	v_or_b32_e32 v99, 56, v0
	v_add_u32_e32 v100, 0x1ce0, v44
	v_or_b32_e32 v101, 58, v0
	v_add_u32_e32 v102, 0x1de8, v44
	v_or_b32_e32 v103, 60, v0
	v_add_u32_e32 v104, 0x1ef0, v44
	v_or_b32_e32 v105, 62, v0
	v_add_u32_e32 v106, 0x1ff8, v44
	v_or_b32_e32 v109, 8, v107
	v_or_b32_e32 v110, 16, v107
	v_or_b32_e32 v111, 24, v107
	v_lshl_add_u64 v[14:15], v[14:15], 0, s[6:7]
	v_mov_b32_e32 v1, v159
	s_mov_b64 s[20:21], 0
	v_mov_b32_e32 v112, v42
	s_branch .LBB0_836

.LBB0_923:
	s_and_b64 vcc, exec, s[6:7]
	s_cbranch_vccz .LBB0_1018
	s_cmpk_lt_i32 s31, 0x80
	s_cbranch_scc1 .LBB0_1018
	s_lshl_b32 s0, s31, 3
	s_add_i32 s4, s0, 0xfffffc00
	v_add_u32_e32 v43, s4, v5
	s_and_b64 s[6:7], s[12:13], exec
	s_movk_i32 s4, 0x2100
	s_cselect_b32 s4, s4, 0x3180
	s_and_b64 s[6:7], s[16:17], exec
	s_cselect_b32 s28, 0xb00, s4
	s_and_b64 s[6:7], s[12:13], exec
	s_movk_i32 s4, 0x4200
	s_cselect_b32 s4, 0x3180, s4
	s_and_b64 s[6:7], s[16:17], exec
	s_cselect_b32 s8, 0x2100, s4
	s_and_b64 s[6:7], s[12:13], exec
	s_cselect_b32 s4, 0x4800, 0
	s_and_b64 s[6:7], s[16:17], exec
	s_cselect_b32 s4, 0x4200, s4
	s_and_b64 s[6:7], s[12:13], exec
	s_cselect_b32 s9, 0x5000, 0
	s_and_b64 s[6:7], s[16:17], exec
	s_cselect_b32 s6, 0x4800, s9
	s_cmp_eq_u32 s86, 11
	s_cbranch_scc0 .Lp19a
	s_movk_i32 s8, 0x3c80
.Lp19a:
	s_cmp_eq_u32 s86, 19
	s_cbranch_scc0 .Lp19b
	s_movk_i32 s28, 0x3c80
.Lp19b:
	s_sub_i32 s29, s8, s28
	s_sub_i32 s36, s6, s4
	v_mov_b32_e32 v42, v156
	s_add_i32 s36, s36, s29
	v_cmp_gt_i32_e32 vcc, s36, v43
	v_and_b32_e32 v3, 63, v42
	s_and_saveexec_b64 s[16:17], vcc
	s_cbranch_execz .LBB0_1004
	v_lshlrev_b32_e32 v0, 8, v42
	v_and_b32_e32 v0, 0xffffc000, v0
	v_add_u32_e32 v1, 0, v0
	v_lshrrev_b32_e32 v0, 5, v3
	v_and_b32_e32 v2, 31, v42
	v_mul_u32_u24_e32 v4, 0x84, v0
	v_lshlrev_b32_e32 v6, 2, v2
	v_add3_u32 v44, v1, v4, v6
	v_lshlrev_b32_e32 v4, 3, v3
	v_and_b32_e32 v4, 56, v4
	v_lshlrev_b32_e32 v158, 1, v4
	v_lshrrev_b32_e32 v107, 3, v3
	v_lshl_add_u64 v[14:15], s[90:91], 0, v[158:159]
	s_mov_b64 s[6:7], 0x1080000
	v_mul_u32_u24_e32 v8, 0x84, v4
	v_lshl_add_u64 v[6:7], v[14:15], 0, s[6:7]
	v_lshlrev_b32_e32 v9, 2, v107
	s_mov_b64 s[6:7], 0x1680000
	v_add3_u32 v108, v1, v8, v9
	v_lshl_add_u64 v[8:9], v[14:15], 0, s[6:7]
	s_mov_b64 s[6:7], 0x6080000
	v_lshl_add_u64 v[10:11], v[14:15], 0, s[6:7]
	s_mov_b64 s[6:7], 0x5e80000
	v_lshl_add_u64 v[12:13], v[14:15], 0, s[6:7]
	s_mov_b64 s[6:7], 0x5c80000
	v_add_u32_e32 v16, s0, v5
	s_sub_i32 s37, s4, s29
	v_or_b32_e32 v45, 2, v0
	v_add_u32_e32 v46, 0x108, v44
	v_or_b32_e32 v47, 4, v0
	v_add_u32_e32 v48, 0x210, v44
	v_or_b32_e32 v49, 6, v0
	v_add_u32_e32 v50, 0x318, v44
	v_or_b32_e32 v51, 8, v0
	v_add_u32_e32 v52, 0x420, v44
	v_or_b32_e32 v53, 10, v0
	v_add_u32_e32 v54, 0x528, v44
	v_or_b32_e32 v55, 12, v0
	v_add_u32_e32 v56, 0x630, v44
	v_or_b32_e32 v57, 14, v0
	v_add_u32_e32 v58, 0x738, v44
	v_or_b32_e32 v59, 16, v0
	v_add_u32_e32 v60, 0x840, v44
	v_or_b32_e32 v61, 18, v0
	v_add_u32_e32 v62, 0x948, v44
	v_or_b32_e32 v63, 20, v0
	v_add_u32_e32 v64, 0xa50, v44
	v_or_b32_e32 v65, 22, v0
	v_add_u32_e32 v66, 0xb58, v44
	v_or_b32_e32 v67, 24, v0
	v_add_u32_e32 v68, 0xc60, v44
	v_or_b32_e32 v69, 26, v0
	v_add_u32_e32 v70, 0xd68, v44
	v_or_b32_e32 v71, 28, v0
	v_add_u32_e32 v72, 0xe70, v44
	v_or_b32_e32 v73, 30, v0
	v_add_u32_e32 v74, 0xf78, v44
	v_or_b32_e32 v75, 32, v0
	v_add_u32_e32 v76, 0x1080, v44
	v_or_b32_e32 v77, 34, v0
	v_add_u32_e32 v78, 0x1188, v44
	v_or_b32_e32 v79, 36, v0
	v_add_u32_e32 v80, 0x1290, v44
	v_or_b32_e32 v81, 38, v0
	v_add_u32_e32 v82, 0x1398, v44
	v_or_b32_e32 v83, 40, v0
	v_add_u32_e32 v84, 0x14a0, v44
	v_or_b32_e32 v85, 42, v0
	v_add_u32_e32 v86, 0x15a8, v44
	v_or_b32_e32 v87, 44, v0
	v_add_u32_e32 v88, 0x16b0, v44
	v_or_b32_e32 v89, 46, v0
	v_add_u32_e32 v90, 0x17b8, v44
	v_or_b32_e32 v91, 48, v0
	v_add_u32_e32 v92, 0x18c0, v44
	v_or_b32_e32 v93, 50, v0
	v_add_u32_e32 v94, 0x19c8, v44
	v_or_b32_e32 v95, 52, v0
	v_add_u32_e32 v96, 0x1ad0, v44
	v_or_b32_e32 v97, 54, v0
	v_add_u32_e32 v98, 0x1bd8, v44
	v_or_b32_e32 v99, 56, v0
	v_add_u32_e32 v100, 0x1ce0, v44
	v_or_b32_e32 v101, 58, v0
	v_add_u32_e32 v102, 0x1de8, v44
	v_or_b32_e32 v103, 60, v0
	v_add_u32_e32 v104, 0x1ef0, v44
	v_or_b32_e32 v105, 62, v0
	v_add_u32_e32 v106, 0x1ff8, v44
	v_or_b32_e32 v109, 8, v107
	v_or_b32_e32 v110, 16, v107
	v_or_b32_e32 v111, 24, v107
	v_lshl_add_u64 v[14:15], v[14:15], 0, s[6:7]
	v_mov_b32_e32 v1, v159
	v_add_u32_e32 v112, 0xffffb200, v16
	s_mov_b64 s[18:19], 0
	s_branch .LBB0_931
